# v8 + hgrn_m2 phase folded into hgrn_m3 range head (one phase and one grid barrier fewer per layer)
# baseline (speedup 1.0000x reference)
; __device__ __forceinline__ unsigned pk2(float lo, float hi) { return cvt_pk_bf16(lo, hi); }
; #define SEAM(k) do { if (IN(k) && IN((k) + 1)) xcd_barrier(bar); } while (0)
; __device__ __forceinline__ void hgrn_m2(Frame& F) {
;     ...
;     for (int gid = F.bx * NTHR + F.tid; gid < 64 * 2048; gid += F.G * NTHR) {
;         const int bh = gid >> 11, e0 = (gid & 2047) * 8, k0 = e0 & 127;
;         float S[8];
;         float z0 = 0.f; asm volatile("" : "+v"(z0));
; #pragma unroll
;         for (int j = 0; j < 8; ++j) S[j] = z0;
;         bf16* p = RS + (size_t)bh * 4 * 16384 + e0; const float* dp = RD + (size_t)bh * 4 * 128 + k0;
; #pragma unroll
;         for (int c = 0; c < 4; ++c) {
;             const u32x4 u = *(const u32x4*)(p + (size_t)c * 16384);
;             const f32x4 d0 = *(const f32x4*)(dp + c * 128), d1 = *(const f32x4*)(dp + c * 128 + 4);
;             u32x4 o; o.x = pk2(S[0], S[1]); o.y = pk2(S[2], S[3]); o.z = pk2(S[4], S[5]); o.w = pk2(S[6], S[7]);
;             *(u32x4*)(p + (size_t)c * 16384) = o;
;             S[0] = d0[0] * S[0] + bflo(u.x); S[1] = d0[1] * S[1] + bfhi(u.x); S[2] = d0[2] * S[2] + bflo(u.y); S[3] = d0[3] * S[3] + bfhi(u.y);
;             S[4] = d1[0] * S[4] + bflo(u.z); S[5] = d1[1] * S[5] + bfhi(u.z); S[6] = d1[2] * S[6] + bflo(u.w); S[7] = d1[3] * S[7] + bfhi(u.w);
;         }
;     }
; __global__ void __launch_bounds__(NTHR, 2) fwd_kernel(Args args) {
;     ...
;         if (IN(pb + 2)) hgrn_m2(F);
;         SEAM(pb + 2);
.LBB0_378:
	s_cmp_le_i32 s50, s2
	s_cselect_b64 s[0:1], -1, 0
	s_and_b64 s[8:9], s[0:1], s[8:9]
	v_readlane_b32 s0, v255, 16
	s_add_i32 s2, s0, 5
	s_cmp_lt_i32 s2, s51
	s_cselect_b64 s[0:1], -1, 0
	s_and_b64 s[6:7], s[8:9], s[0:1]

; __device__ __forceinline__ unsigned pk2(float lo, float hi) { return cvt_pk_bf16(lo, hi); }
; __device__ __forceinline__ void hgrn_m2(Frame& F) {
;     ...
;         bf16* p = RS + (size_t)bh * 4 * 16384 + e0; const float* dp = RD + (size_t)bh * 4 * 128 + k0;
; #pragma unroll
;         for (int c = 0; c < 4; ++c) {
;             const u32x4 u = *(const u32x4*)(p + (size_t)c * 16384);
;             const f32x4 d0 = *(const f32x4*)(dp + c * 128), d1 = *(const f32x4*)(dp + c * 128 + 4);
;             u32x4 o; o.x = pk2(S[0], S[1]); o.y = pk2(S[2], S[3]); o.z = pk2(S[4], S[5]); o.w = pk2(S[6], S[7]);
;             *(u32x4*)(p + (size_t)c * 16384) = o;
;             S[0] = d0[0] * S[0] + bflo(u.x); S[1] = d0[1] * S[1] + bfhi(u.x); S[2] = d0[2] * S[2] + bflo(u.y); S[3] = d0[3] * S[3] + bfhi(u.y);
;             S[4] = d1[0] * S[4] + bflo(u.z); S[5] = d1[1] * S[5] + bfhi(u.z); S[6] = d1[2] * S[6] + bflo(u.w); S[7] = d1[3] * S[7] + bfhi(u.w);
;         }
; __device__ __forceinline__ void hgrn_m3(Frame& F) {
;     ...
;           for (int g4 = 0; g4 < 4; ++g4) { const u32x2 w = *(const u32x2*)(RS + (size_t)rg * 16384 + (size_t)(32 * (vt0 + x) + r32) * 128 + 32 * kt + 8 * g4 + 4 * hi5);
;               st[x][4 * g4] = bflo(w.x); st[x][4 * g4 + 1] = bfhi(w.x); st[x][4 * g4 + 2] = bflo(w.y); st[x][4 * g4 + 3] = bfhi(w.y); }
.LBB0_443:
	s_and_b32 s1, s0, 3
	s_sub_i32 s24, s0, s1
	s_lshl_b32 s12, s24, 9
	s_lshl_b32 s24, s24, 15
	v_readlane_b32 s7, v255, 19
	v_readlane_b32 s16, v255, 20
	s_add_u32 s24, s7, s24
	s_addc_u32 s25, s16, 0
	s_add_u32 s24, s24, 0x4900000
	s_addc_u32 s25, s25, 0
	s_add_u32 s12, s7, s12
	s_addc_u32 s13, s16, 0
	s_add_u32 s12, s12, 0x5100000
	s_addc_u32 s13, s13, 0
	v_and_b32_e32 v68, 31, v0
	v_lshlrev_b32_e32 v68, 8, v68
	v_bfe_u32 v69, v0, 6, 1
	v_lshl_add_u32 v68, v69, 14, v68
	v_lshl_add_u32 v68, v72, 6, v68
	v_bfe_u32 v69, v0, 5, 1
	v_lshl_add_u32 v68, v69, 3, v68
	v_add_u32_e32 v70, 0x2000, v68
	v_lshlrev_b32_e32 v69, 4, v69
	v_lshl_add_u32 v69, v72, 7, v69
	s_cmp_eq_u32 s1, 0
	s_cbranch_scc1 .Lmy_m3_s0
	global_load_dwordx2 v[34:35], v68, s[24:25]
	global_load_dwordx2 v[36:37], v68, s[24:25] offset:16
	global_load_dwordx2 v[38:39], v68, s[24:25] offset:32
	global_load_dwordx2 v[40:41], v68, s[24:25] offset:48
	global_load_dwordx2 v[42:43], v70, s[24:25]
	global_load_dwordx2 v[44:45], v70, s[24:25] offset:16
	global_load_dwordx2 v[46:47], v70, s[24:25] offset:32
	global_load_dwordx2 v[48:49], v70, s[24:25] offset:48
	s_waitcnt vmcnt(0)
	v_lshlrev_b32_e32 v2, 16, v34
	v_and_b32_e32 v3, 0xffff0000, v34
	v_lshlrev_b32_e32 v4, 16, v35
	v_and_b32_e32 v5, 0xffff0000, v35
	v_lshlrev_b32_e32 v6, 16, v36
	v_and_b32_e32 v7, 0xffff0000, v36
	v_lshlrev_b32_e32 v8, 16, v37
	v_and_b32_e32 v9, 0xffff0000, v37
	v_lshlrev_b32_e32 v10, 16, v38
	v_and_b32_e32 v11, 0xffff0000, v38
	v_lshlrev_b32_e32 v12, 16, v39
	v_and_b32_e32 v13, 0xffff0000, v39
	v_lshlrev_b32_e32 v14, 16, v40
	v_and_b32_e32 v15, 0xffff0000, v40
	v_lshlrev_b32_e32 v16, 16, v41
	v_and_b32_e32 v17, 0xffff0000, v41
	v_lshlrev_b32_e32 v18, 16, v42
	v_and_b32_e32 v19, 0xffff0000, v42
	v_lshlrev_b32_e32 v20, 16, v43
	v_and_b32_e32 v21, 0xffff0000, v43
	v_lshlrev_b32_e32 v22, 16, v44
	v_and_b32_e32 v23, 0xffff0000, v44
	v_lshlrev_b32_e32 v24, 16, v45
	v_and_b32_e32 v25, 0xffff0000, v45
	v_lshlrev_b32_e32 v26, 16, v46
	v_and_b32_e32 v27, 0xffff0000, v46
	v_lshlrev_b32_e32 v28, 16, v47
	v_and_b32_e32 v29, 0xffff0000, v47
	v_lshlrev_b32_e32 v30, 16, v48
	v_and_b32_e32 v31, 0xffff0000, v48
	v_lshlrev_b32_e32 v32, 16, v49
	v_and_b32_e32 v33, 0xffff0000, v49
	v_add_f32_e32 v2, 0, v2
	v_add_f32_e32 v3, 0, v3
	v_add_f32_e32 v4, 0, v4
	v_add_f32_e32 v5, 0, v5
	v_add_f32_e32 v6, 0, v6
	v_add_f32_e32 v7, 0, v7
	v_add_f32_e32 v8, 0, v8
	v_add_f32_e32 v9, 0, v9
	v_add_f32_e32 v10, 0, v10
	v_add_f32_e32 v11, 0, v11
	v_add_f32_e32 v12, 0, v12
	v_add_f32_e32 v13, 0, v13
	v_add_f32_e32 v14, 0, v14
	v_add_f32_e32 v15, 0, v15
	v_add_f32_e32 v16, 0, v16
	v_add_f32_e32 v17, 0, v17
	v_add_f32_e32 v18, 0, v18
	v_add_f32_e32 v19, 0, v19
	v_add_f32_e32 v20, 0, v20
	v_add_f32_e32 v21, 0, v21
	v_add_f32_e32 v22, 0, v22
	v_add_f32_e32 v23, 0, v23
	v_add_f32_e32 v24, 0, v24
	v_add_f32_e32 v25, 0, v25
	v_add_f32_e32 v26, 0, v26
	v_add_f32_e32 v27, 0, v27
	v_add_f32_e32 v28, 0, v28
	v_add_f32_e32 v29, 0, v29
	v_add_f32_e32 v30, 0, v30
	v_add_f32_e32 v31, 0, v31
	v_add_f32_e32 v32, 0, v32
	v_add_f32_e32 v33, 0, v33
	s_cmp_eq_u32 s1, 1
	s_cbranch_scc1 .Lmy_m3_round
	s_add_u32 s24, s24, 0x8000
	s_addc_u32 s25, s25, 0
	s_add_u32 s12, s12, 0x200
	s_addc_u32 s13, s13, 0
	global_load_dwordx2 v[34:35], v68, s[24:25]
	global_load_dwordx2 v[36:37], v68, s[24:25] offset:16
	global_load_dwordx2 v[38:39], v68, s[24:25] offset:32
	global_load_dwordx2 v[40:41], v68, s[24:25] offset:48
	global_load_dwordx2 v[42:43], v70, s[24:25]
	global_load_dwordx2 v[44:45], v70, s[24:25] offset:16
	global_load_dwordx2 v[46:47], v70, s[24:25] offset:32
	global_load_dwordx2 v[48:49], v70, s[24:25] offset:48
	global_load_dwordx4 v[50:53], v69, s[12:13]
	global_load_dwordx4 v[54:57], v69, s[12:13] offset:32
	global_load_dwordx4 v[58:61], v69, s[12:13] offset:64
	global_load_dwordx4 v[62:65], v69, s[12:13] offset:96
	s_waitcnt vmcnt(0)
	v_lshlrev_b32_e32 v71, 16, v34
	v_fma_f32 v2, v2, v50, v71
	v_and_b32_e32 v71, 0xffff0000, v34
	v_fma_f32 v3, v3, v51, v71
	v_lshlrev_b32_e32 v71, 16, v35
	v_fma_f32 v4, v4, v52, v71
	v_and_b32_e32 v71, 0xffff0000, v35
	v_fma_f32 v5, v5, v53, v71
	v_lshlrev_b32_e32 v71, 16, v36
	v_fma_f32 v6, v6, v54, v71
	v_and_b32_e32 v71, 0xffff0000, v36
	v_fma_f32 v7, v7, v55, v71
	v_lshlrev_b32_e32 v71, 16, v37
	v_fma_f32 v8, v8, v56, v71
	v_and_b32_e32 v71, 0xffff0000, v37
	v_fma_f32 v9, v9, v57, v71
	v_lshlrev_b32_e32 v71, 16, v38
	v_fma_f32 v10, v10, v58, v71
	v_and_b32_e32 v71, 0xffff0000, v38
	v_fma_f32 v11, v11, v59, v71
	v_lshlrev_b32_e32 v71, 16, v39
	v_fma_f32 v12, v12, v60, v71
	v_and_b32_e32 v71, 0xffff0000, v39
	v_fma_f32 v13, v13, v61, v71
	v_lshlrev_b32_e32 v71, 16, v40
	v_fma_f32 v14, v14, v62, v71
	v_and_b32_e32 v71, 0xffff0000, v40
	v_fma_f32 v15, v15, v63, v71
	v_lshlrev_b32_e32 v71, 16, v41
	v_fma_f32 v16, v16, v64, v71
	v_and_b32_e32 v71, 0xffff0000, v41
	v_fma_f32 v17, v17, v65, v71
	v_lshlrev_b32_e32 v71, 16, v42
	v_fma_f32 v18, v18, v50, v71
	v_and_b32_e32 v71, 0xffff0000, v42
	v_fma_f32 v19, v19, v51, v71
	v_lshlrev_b32_e32 v71, 16, v43
	v_fma_f32 v20, v20, v52, v71
	v_and_b32_e32 v71, 0xffff0000, v43
	v_fma_f32 v21, v21, v53, v71
	v_lshlrev_b32_e32 v71, 16, v44
	v_fma_f32 v22, v22, v54, v71
	v_and_b32_e32 v71, 0xffff0000, v44
	v_fma_f32 v23, v23, v55, v71
	v_lshlrev_b32_e32 v71, 16, v45
	v_fma_f32 v24, v24, v56, v71
	v_and_b32_e32 v71, 0xffff0000, v45
	v_fma_f32 v25, v25, v57, v71
	v_lshlrev_b32_e32 v71, 16, v46
	v_fma_f32 v26, v26, v58, v71
	v_and_b32_e32 v71, 0xffff0000, v46
	v_fma_f32 v27, v27, v59, v71
	v_lshlrev_b32_e32 v71, 16, v47
	v_fma_f32 v28, v28, v60, v71
	v_and_b32_e32 v71, 0xffff0000, v47
	v_fma_f32 v29, v29, v61, v71
	v_lshlrev_b32_e32 v71, 16, v48
	v_fma_f32 v30, v30, v62, v71
	v_and_b32_e32 v71, 0xffff0000, v48
	v_fma_f32 v31, v31, v63, v71
	v_lshlrev_b32_e32 v71, 16, v49
	v_fma_f32 v32, v32, v64, v71
	v_and_b32_e32 v71, 0xffff0000, v49
	v_fma_f32 v33, v33, v65, v71
	s_cmp_eq_u32 s1, 2
	s_cbranch_scc1 .Lmy_m3_round
; __device__ __forceinline__ unsigned pk2(float lo, float hi) { return cvt_pk_bf16(lo, hi); }
; __device__ __forceinline__ void hgrn_m2(Frame& F) {
;     ...
;             const u32x4 u = *(const u32x4*)(p + (size_t)c * 16384);
;             const f32x4 d0 = *(const f32x4*)(dp + c * 128), d1 = *(const f32x4*)(dp + c * 128 + 4);
;             u32x4 o; o.x = pk2(S[0], S[1]); o.y = pk2(S[2], S[3]); o.z = pk2(S[4], S[5]); o.w = pk2(S[6], S[7]);
;             *(u32x4*)(p + (size_t)c * 16384) = o;
;             S[0] = d0[0] * S[0] + bflo(u.x); S[1] = d0[1] * S[1] + bfhi(u.x); S[2] = d0[2] * S[2] + bflo(u.y); S[3] = d0[3] * S[3] + bfhi(u.y);
;             S[4] = d1[0] * S[4] + bflo(u.z); S[5] = d1[1] * S[5] + bfhi(u.z); S[6] = d1[2] * S[6] + bflo(u.w); S[7] = d1[3] * S[7] + bfhi(u.w);
;         }
; __device__ __forceinline__ void hgrn_m3(Frame& F) {
;     ...
;           for (int g4 = 0; g4 < 4; ++g4) { const u32x2 w = *(const u32x2*)(RS + (size_t)rg * 16384 + (size_t)(32 * (vt0 + x) + r32) * 128 + 32 * kt + 8 * g4 + 4 * hi5);
;               st[x][4 * g4] = bflo(w.x); st[x][4 * g4 + 1] = bfhi(w.x); st[x][4 * g4 + 2] = bflo(w.y); st[x][4 * g4 + 3] = bfhi(w.y); }
	s_add_u32 s24, s24, 0x8000
	s_addc_u32 s25, s25, 0
	s_add_u32 s12, s12, 0x200
	s_addc_u32 s13, s13, 0
	global_load_dwordx2 v[34:35], v68, s[24:25]
	global_load_dwordx2 v[36:37], v68, s[24:25] offset:16
	global_load_dwordx2 v[38:39], v68, s[24:25] offset:32
	global_load_dwordx2 v[40:41], v68, s[24:25] offset:48
	global_load_dwordx2 v[42:43], v70, s[24:25]
	global_load_dwordx2 v[44:45], v70, s[24:25] offset:16
	global_load_dwordx2 v[46:47], v70, s[24:25] offset:32
	global_load_dwordx2 v[48:49], v70, s[24:25] offset:48
	global_load_dwordx4 v[50:53], v69, s[12:13]
	global_load_dwordx4 v[54:57], v69, s[12:13] offset:32
	global_load_dwordx4 v[58:61], v69, s[12:13] offset:64
	global_load_dwordx4 v[62:65], v69, s[12:13] offset:96
	s_waitcnt vmcnt(0)
	v_lshlrev_b32_e32 v71, 16, v34
	v_fma_f32 v2, v2, v50, v71
	v_and_b32_e32 v71, 0xffff0000, v34
	v_fma_f32 v3, v3, v51, v71
	v_lshlrev_b32_e32 v71, 16, v35
	v_fma_f32 v4, v4, v52, v71
	v_and_b32_e32 v71, 0xffff0000, v35
	v_fma_f32 v5, v5, v53, v71
	v_lshlrev_b32_e32 v71, 16, v36
	v_fma_f32 v6, v6, v54, v71
	v_and_b32_e32 v71, 0xffff0000, v36
	v_fma_f32 v7, v7, v55, v71
	v_lshlrev_b32_e32 v71, 16, v37
	v_fma_f32 v8, v8, v56, v71
	v_and_b32_e32 v71, 0xffff0000, v37
	v_fma_f32 v9, v9, v57, v71
	v_lshlrev_b32_e32 v71, 16, v38
	v_fma_f32 v10, v10, v58, v71
	v_and_b32_e32 v71, 0xffff0000, v38
	v_fma_f32 v11, v11, v59, v71
	v_lshlrev_b32_e32 v71, 16, v39
	v_fma_f32 v12, v12, v60, v71
	v_and_b32_e32 v71, 0xffff0000, v39
	v_fma_f32 v13, v13, v61, v71
	v_lshlrev_b32_e32 v71, 16, v40
	v_fma_f32 v14, v14, v62, v71
	v_and_b32_e32 v71, 0xffff0000, v40
	v_fma_f32 v15, v15, v63, v71
	v_lshlrev_b32_e32 v71, 16, v41
	v_fma_f32 v16, v16, v64, v71
	v_and_b32_e32 v71, 0xffff0000, v41
	v_fma_f32 v17, v17, v65, v71
	v_lshlrev_b32_e32 v71, 16, v42
	v_fma_f32 v18, v18, v50, v71
	v_and_b32_e32 v71, 0xffff0000, v42
	v_fma_f32 v19, v19, v51, v71
	v_lshlrev_b32_e32 v71, 16, v43
	v_fma_f32 v20, v20, v52, v71
	v_and_b32_e32 v71, 0xffff0000, v43
	v_fma_f32 v21, v21, v53, v71
	v_lshlrev_b32_e32 v71, 16, v44
	v_fma_f32 v22, v22, v54, v71
	v_and_b32_e32 v71, 0xffff0000, v44
	v_fma_f32 v23, v23, v55, v71
	v_lshlrev_b32_e32 v71, 16, v45
	v_fma_f32 v24, v24, v56, v71
	v_and_b32_e32 v71, 0xffff0000, v45
	v_fma_f32 v25, v25, v57, v71
	v_lshlrev_b32_e32 v71, 16, v46
	v_fma_f32 v26, v26, v58, v71
	v_and_b32_e32 v71, 0xffff0000, v46
	v_fma_f32 v27, v27, v59, v71
	v_lshlrev_b32_e32 v71, 16, v47
	v_fma_f32 v28, v28, v60, v71
	v_and_b32_e32 v71, 0xffff0000, v47
	v_fma_f32 v29, v29, v61, v71
	v_lshlrev_b32_e32 v71, 16, v48
	v_fma_f32 v30, v30, v62, v71
	v_and_b32_e32 v71, 0xffff0000, v48
	v_fma_f32 v31, v31, v63, v71
	v_lshlrev_b32_e32 v71, 16, v49
	v_fma_f32 v32, v32, v64, v71
	v_and_b32_e32 v71, 0xffff0000, v49
	v_fma_f32 v33, v33, v65, v71
.Lmy_m3_round:
	v_cvt_pk_bf16_f32 v71, v2, v3
	v_lshlrev_b32_e32 v2, 16, v71
	v_and_b32_e32 v3, 0xffff0000, v71
	v_cvt_pk_bf16_f32 v71, v4, v5
	v_lshlrev_b32_e32 v4, 16, v71
	v_and_b32_e32 v5, 0xffff0000, v71
	v_cvt_pk_bf16_f32 v71, v6, v7
	v_lshlrev_b32_e32 v6, 16, v71
	v_and_b32_e32 v7, 0xffff0000, v71
	v_cvt_pk_bf16_f32 v71, v8, v9
	v_lshlrev_b32_e32 v8, 16, v71
	v_and_b32_e32 v9, 0xffff0000, v71
	v_cvt_pk_bf16_f32 v71, v10, v11
	v_lshlrev_b32_e32 v10, 16, v71
	v_and_b32_e32 v11, 0xffff0000, v71
	v_cvt_pk_bf16_f32 v71, v12, v13
	v_lshlrev_b32_e32 v12, 16, v71
	v_and_b32_e32 v13, 0xffff0000, v71
	v_cvt_pk_bf16_f32 v71, v14, v15
	v_lshlrev_b32_e32 v14, 16, v71
	v_and_b32_e32 v15, 0xffff0000, v71
	v_cvt_pk_bf16_f32 v71, v16, v17
	v_lshlrev_b32_e32 v16, 16, v71
	v_and_b32_e32 v17, 0xffff0000, v71
	v_cvt_pk_bf16_f32 v71, v18, v19
	v_lshlrev_b32_e32 v18, 16, v71
	v_and_b32_e32 v19, 0xffff0000, v71
	v_cvt_pk_bf16_f32 v71, v20, v21
	v_lshlrev_b32_e32 v20, 16, v71
	v_and_b32_e32 v21, 0xffff0000, v71
	v_cvt_pk_bf16_f32 v71, v22, v23
	v_lshlrev_b32_e32 v22, 16, v71
	v_and_b32_e32 v23, 0xffff0000, v71
	v_cvt_pk_bf16_f32 v71, v24, v25
	v_lshlrev_b32_e32 v24, 16, v71
	v_and_b32_e32 v25, 0xffff0000, v71
	v_cvt_pk_bf16_f32 v71, v26, v27
	v_lshlrev_b32_e32 v26, 16, v71
	v_and_b32_e32 v27, 0xffff0000, v71
	v_cvt_pk_bf16_f32 v71, v28, v29
	v_lshlrev_b32_e32 v28, 16, v71
	v_and_b32_e32 v29, 0xffff0000, v71
	v_cvt_pk_bf16_f32 v71, v30, v31
	v_lshlrev_b32_e32 v30, 16, v71
	v_and_b32_e32 v31, 0xffff0000, v71
	v_cvt_pk_bf16_f32 v71, v32, v33
	v_lshlrev_b32_e32 v32, 16, v71
	v_and_b32_e32 v33, 0xffff0000, v71
	s_branch .Lmy_m3_sdone
.Lmy_m3_s0:
	v_mov_b32_e32 v2, 0
	v_mov_b32_e32 v3, 0
	v_mov_b32_e32 v4, 0
	v_mov_b32_e32 v5, 0
	v_mov_b32_e32 v6, 0
	v_mov_b32_e32 v7, 0
	v_mov_b32_e32 v8, 0
	v_mov_b32_e32 v9, 0
	v_mov_b32_e32 v10, 0
	v_mov_b32_e32 v11, 0
	v_mov_b32_e32 v12, 0
	v_mov_b32_e32 v13, 0
	v_mov_b32_e32 v14, 0
	v_mov_b32_e32 v15, 0
	v_mov_b32_e32 v16, 0
	v_mov_b32_e32 v17, 0
	v_mov_b32_e32 v18, 0
	v_mov_b32_e32 v19, 0
	v_mov_b32_e32 v20, 0
	v_mov_b32_e32 v21, 0
	v_mov_b32_e32 v22, 0
	v_mov_b32_e32 v23, 0
	v_mov_b32_e32 v24, 0
	v_mov_b32_e32 v25, 0
	v_mov_b32_e32 v26, 0
	v_mov_b32_e32 v27, 0
	v_mov_b32_e32 v28, 0
	v_mov_b32_e32 v29, 0
	v_mov_b32_e32 v30, 0
	v_mov_b32_e32 v31, 0
	v_mov_b32_e32 v32, 0
	v_mov_b32_e32 v33, 0
.Lmy_m3_sdone:
	s_waitcnt vmcnt(0)
	s_ashr_i32 s1, s0, 31
	s_lshl_b32 s1, s0, 5
	s_ashr_i32 s12, s0, 4
	s_and_b32 s7, s1, 0x180
	v_readlane_b32 s1, v253, 36
	s_ashr_i32 s13, s12, 31
	s_lshl_b32 s16, s7, 1
	s_add_i32 s0, s0, s1
	s_lshl_b64 s[12:13], s[12:13], 12
	v_lshl_add_u64 v[96:97], v[80:81], 0, s[16:17]
	s_lshl_b32 s1, s0, 4
	s_mov_b32 s77, 0
	s_lshl_b32 s16, s7, 1
	s_mov_b32 s86, s6
	s_branch .LBB0_445
